# st11 without the L2 writeback at the first grid barrier (every P0 output is already stored write-through)
# speedup vs baseline: 1.0041x; 1.0041x over previous
.LBB0_74:
	s_andn2_saveexec_b64 s[4:5], s[4:5]
	s_cbranch_execz .LBB0_94
	s_mov_b64 s[4:5], exec
	s_nop 0
	s_waitcnt lgkmcnt(0)
	s_waitcnt vmcnt(0)
	buffer_inv sc1
	v_mbcnt_lo_u32_b32 v3, s4, 0
	v_mbcnt_hi_u32_b32 v3, s5, v3
	v_cmp_eq_u32_e32 vcc, 0, v3
	s_and_saveexec_b64 s[6:7], vcc
	s_cbranch_execz .LBB0_77
	s_bcnt1_i32_b64 s4, s[4:5]
	v_mov_b32_e32 v4, 0x15ee3000
	v_mov_b32_e32 v5, s4
	global_atomic_add v4, v4, v5, s[62:63] offset:1024 sc0
